# P0 convert_bf16(mem): 4 serialized load/store iterations batched (256-block fast path)
# speedup vs baseline: 1.0137x; 1.0062x over previous
; DI int otid() { int t = __builtin_amdgcn_workitem_id_x(); asm volatile("" : "+v"(t)); return t; }
; DI unsigned pack2(float a, float b) { const f32x2 v = {a, b}; return __builtin_bit_cast(unsigned, __builtin_convertvector(v, bf16v2)); }
; DI void convert_bf16(const float* __restrict__ src, u16* __restrict__ dst, size_t n4) {
;   const size_t stride = (size_t)gridDim.x * 512;
;   for (size_t i = (size_t)blockIdx.x * 512 + otid(); i < n4; i += stride) {
;     float4 v = ((const float4*)src)[i];
;     uint2 o; o.x = pack2(v.x, v.y); o.y = pack2(v.z, v.w);
;     ((uint2*)dst)[i] = o;
;   }
.LBB0_150:
	s_or_b64 exec, exec, s[8:9]
	v_mov_b32_e32 v6, v222
	s_mov_b64 s[2:3], 0x80000
	v_ashrrev_i32_e32 v7, 31, v6
	v_lshl_add_u64 v[2:3], s[6:7], 0, v[6:7]
	v_cmp_gt_u64_e32 vcc, s[2:3], v[2:3]
	s_and_saveexec_b64 s[6:7], vcc
	s_cbranch_execz .LBB0_153
	s_lshl_b64 s[2:3], s[94:95], 13
	s_add_u32 s2, s54, s2
	s_addc_u32 s3, s55, s3
	v_lshl_add_u64 v[4:5], v[6:7], 4, s[2:3]
	s_lshl_b64 s[8:9], s[4:5], 13
	s_lshl_b64 s[2:3], s[94:95], 12
	s_add_u32 s2, s68, s2
	s_addc_u32 s3, s69, s3
	v_lshl_add_u64 v[6:7], v[6:7], 3, s[2:3]
	s_mov_b64 s[2:3], 0x1700000
	v_lshl_add_u64 v[4:5], v[4:5], 0, 8
	v_lshl_add_u64 v[6:7], v[6:7], 0, s[2:3]
	s_lshl_b64 s[4:5], s[4:5], 12
	s_mov_b64 s[10:11], 0
	s_mov_b64 s[12:13], 0x7ffff
	s_cmpk_lg_u32 s70, 0x100
	s_cbranch_scc1 .LBB0_152
	global_load_dwordx4 v[8:11], v[4:5], off offset:-8
	v_lshl_add_u64 v[4:5], v[4:5], 0, s[8:9]
	global_load_dwordx4 v[12:15], v[4:5], off offset:-8
	v_lshl_add_u64 v[4:5], v[4:5], 0, s[8:9]
	global_load_dwordx4 v[16:19], v[4:5], off offset:-8
	v_lshl_add_u64 v[4:5], v[4:5], 0, s[8:9]
	global_load_dwordx4 v[20:23], v[4:5], off offset:-8
	s_waitcnt vmcnt(3)
	v_cvt_pk_bf16_f32 v8, v8, v9
	v_cvt_pk_bf16_f32 v9, v10, v11
	global_store_dwordx2 v[6:7], v[8:9], off
	v_lshl_add_u64 v[6:7], v[6:7], 0, s[4:5]
	s_waitcnt vmcnt(3)
	v_cvt_pk_bf16_f32 v12, v12, v13
	v_cvt_pk_bf16_f32 v13, v14, v15
	global_store_dwordx2 v[6:7], v[12:13], off
	v_lshl_add_u64 v[6:7], v[6:7], 0, s[4:5]
	s_waitcnt vmcnt(3)
	v_cvt_pk_bf16_f32 v16, v16, v17
	v_cvt_pk_bf16_f32 v17, v18, v19
	global_store_dwordx2 v[6:7], v[16:17], off
	v_lshl_add_u64 v[6:7], v[6:7], 0, s[4:5]
	s_waitcnt vmcnt(3)
	v_cvt_pk_bf16_f32 v20, v20, v21
	v_cvt_pk_bf16_f32 v21, v22, v23
	global_store_dwordx2 v[6:7], v[20:21], off
	s_branch .LBB0_153
